# mixer A: whole-tile key-range mask for edge waves (then mask-free path), QK second half double-buffered K fragments
# speedup vs baseline: 1.0044x; 1.0044x over previous
; #define LAS __attribute__((address_space(3)))
; #define MFMA32(a, b, c) __builtin_amdgcn_mfma_f32_32x32x16_bf16((a), (b), (c), 0, 0, 0)
; #define A_LOADQ(SB) do { if (active) { int pb, i0, rbq; A_QPOS(SB, pb, i0, rbq); const bf16* qr = Qg + (size_t)(pb + i0 + ql) * 64 + 8 * hh; \
;                 _Pragma("unroll") for (int s = 0; s < 4; ++s) qf[s] = *(const bf16x8*)(qr + 16 * s); } } while (0)
; __device__ __forceinline__ void attnA_unit(LAS unsigned char* lds, const Args& A, int unit) {
;     ...
;                 for (int s = 0; s < 4; ++s)
; #pragma unroll
;                     for (int kt = 0; kt < 5; ++kt) S[kt] = MFMA32(*(const LAS bf16x8*)(kt_l + (rb + 32 * kt + ql) * AST + hh * 16 + 32 * s), qf[s], S[kt]);
;                 asm volatile("" : "+v"(S[4][15]));
;                 if (sb + 1 < nsb) { A_LOADQ(sb + 1); }
.LBB0_295:
	v_add_u32_e32 v0, v163, v144
	v_mad_u64_u32 v[170:171], s[22:23], v0, s88, v[148:149]
	ds_read_b128 v[0:3], v170 offset:4096
	ds_read_b128 v[166:169], v170 offset:4128
	s_andn2_b64 vcc, exec, s[82:83]
	s_waitcnt vmcnt(11) lgkmcnt(1)
	v_mfma_f32_32x32x16_bf16 v[64:79], v[0:3], v[80:83], 0
	ds_read_b128 v[0:3], v170 offset:8704
	s_waitcnt vmcnt(10) lgkmcnt(1)
	v_mfma_f32_32x32x16_bf16 v[64:79], v[166:169], v[84:87], v[64:79]
	ds_read_b128 v[166:169], v170 offset:8736
	s_waitcnt lgkmcnt(1)
	v_mfma_f32_32x32x16_bf16 v[48:63], v[0:3], v[80:83], 0
	ds_read_b128 v[0:3], v170 offset:13312
	s_waitcnt lgkmcnt(1)
	v_mfma_f32_32x32x16_bf16 v[48:63], v[166:169], v[84:87], v[48:63]
	ds_read_b128 v[166:169], v170 offset:13344
	s_waitcnt lgkmcnt(1)
	v_mfma_f32_32x32x16_bf16 v[32:47], v[0:3], v[80:83], 0
	ds_read_b128 v[0:3], v170 offset:17920
	s_waitcnt lgkmcnt(1)
	v_mfma_f32_32x32x16_bf16 v[32:47], v[166:169], v[84:87], v[32:47]
	ds_read_b128 v[166:169], v170 offset:17952
	s_waitcnt lgkmcnt(1)
	v_mfma_f32_32x32x16_bf16 v[16:31], v[0:3], v[80:83], 0
	ds_read_b128 v[0:3], v170 offset:22528
	s_waitcnt lgkmcnt(1)
	v_mfma_f32_32x32x16_bf16 v[16:31], v[166:169], v[84:87], v[16:31]
	ds_read_b128 v[166:169], v170 offset:22560
	s_waitcnt lgkmcnt(1)
	v_mfma_f32_32x32x16_bf16 v[0:15], v[0:3], v[80:83], 0
	s_waitcnt lgkmcnt(0)
	v_mfma_f32_32x32x16_bf16 v[0:15], v[166:169], v[84:87], v[0:15]
	ds_read_b128 v[166:169], v170 offset:4160
	ds_read_b128 v[172:175], v170 offset:8768
	s_waitcnt vmcnt(9) lgkmcnt(1)
	v_mfma_f32_32x32x16_bf16 v[64:79], v[166:169], v[88:91], v[64:79]
	ds_read_b128 v[166:169], v170 offset:13376
	s_waitcnt lgkmcnt(1)
	v_mfma_f32_32x32x16_bf16 v[48:63], v[172:175], v[88:91], v[48:63]
	ds_read_b128 v[172:175], v170 offset:17984
	s_waitcnt lgkmcnt(1)
	v_mfma_f32_32x32x16_bf16 v[32:47], v[166:169], v[88:91], v[32:47]
	ds_read_b128 v[166:169], v170 offset:22592
	s_waitcnt lgkmcnt(1)
	v_mfma_f32_32x32x16_bf16 v[16:31], v[172:175], v[88:91], v[16:31]
	ds_read_b128 v[172:175], v170 offset:4192
	s_waitcnt lgkmcnt(1)
	v_mfma_f32_32x32x16_bf16 v[0:15], v[166:169], v[88:91], v[0:15]
	ds_read_b128 v[166:169], v170 offset:8800
	s_waitcnt vmcnt(8) lgkmcnt(1)
	v_mfma_f32_32x32x16_bf16 v[64:79], v[172:175], v[92:95], v[64:79]
	ds_read_b128 v[172:175], v170 offset:13408
	s_waitcnt lgkmcnt(1)
	v_mfma_f32_32x32x16_bf16 v[48:63], v[166:169], v[92:95], v[48:63]
	ds_read_b128 v[166:169], v170 offset:22624
	s_waitcnt lgkmcnt(1)
	v_mfma_f32_32x32x16_bf16 v[32:47], v[172:175], v[92:95], v[32:47]
	ds_read_b128 v[172:175], v170 offset:18016
	s_waitcnt lgkmcnt(1)
	v_mfma_f32_32x32x16_bf16 v[0:15], v[166:169], v[92:95], v[0:15]
	s_waitcnt lgkmcnt(0)
	v_mfma_f32_32x32x16_bf16 v[16:31], v[172:175], v[92:95], v[16:31]
	s_cbranch_vccnz .LBB0_301
	s_and_b64 vcc, exec, s[42:43]
	s_cbranch_vccz .LBB0_298
	s_and_b64 s[22:23], s[76:77], exec
	s_cselect_b32 s24, 0, s97
	s_add_i32 s25, s90, 0x100
	s_and_b64 s[22:23], s[76:77], exec
	s_cselect_b32 s22, s25, s91
	v_add_u32_e32 v80, s22, v155
	v_mov_b32_e32 v81, s24
	s_cbranch_execz .LBB0_299
	s_branch .LBB0_300

; __device__ __forceinline__ int crow(int i, int h) { return (i & 3) + 8 * (i >> 2) + 4 * h; }
; __device__ __forceinline__ void attnA_unit(LAS unsigned char* lds, const Args& A, int unit) {
;     ...
;                 const bool edge = (i0 < 64) || (i0 + 96 > L);
;                 float mxp[2] = {-1e30f, -1e30f};
; #pragma unroll
;                 for (int kt = 0; kt < 5; ++kt)
; #pragma unroll
;                     for (int i = 0; i < 16; ++i) {
;                         const int cr = crow(i, 0);
;                         float v = S[kt][i] * QK_C + bl[32 * kt + cr + 4 * hh - ql + 32];
;                         if (edge) { const int kidx = i0 - 64 + 32 * kt + cr + 4 * hh; if (kidx < 0 || kidx >= L) v = -1e30f; }
;                         S[kt][i] = v; mxp[i & 1] = fmaxf(mxp[i & 1], v);
;                     }
.LmixA_medium:
	v_readfirstlane_b32 s22, v162
	s_nop 7
	s_nop 3
	s_cmp_lt_i32 s22, 33
	s_cbranch_scc0 .LmixA_m0
	v_mov_b32_e32 v64, v221
	v_mov_b32_e32 v65, v221
	v_mov_b32_e32 v66, v221
	v_mov_b32_e32 v67, v221
	v_mov_b32_e32 v68, v221
	v_mov_b32_e32 v69, v221
	v_mov_b32_e32 v70, v221
	v_mov_b32_e32 v71, v221
	v_mov_b32_e32 v72, v221
	v_mov_b32_e32 v73, v221
	v_mov_b32_e32 v74, v221
	v_mov_b32_e32 v75, v221
	v_mov_b32_e32 v76, v221
	v_mov_b32_e32 v77, v221
	v_mov_b32_e32 v78, v221
	v_mov_b32_e32 v79, v221
.LmixA_m0:
	s_cmp_lt_i32 s22, 1
	s_cbranch_scc0 .LmixA_m1
	v_mov_b32_e32 v48, v221
	v_mov_b32_e32 v49, v221
	v_mov_b32_e32 v50, v221
	v_mov_b32_e32 v51, v221
	v_mov_b32_e32 v52, v221
	v_mov_b32_e32 v53, v221
	v_mov_b32_e32 v54, v221
	v_mov_b32_e32 v55, v221
	v_mov_b32_e32 v56, v221
	v_mov_b32_e32 v57, v221
	v_mov_b32_e32 v58, v221
	v_mov_b32_e32 v59, v221
	v_mov_b32_e32 v60, v221
	v_mov_b32_e32 v61, v221
	v_mov_b32_e32 v62, v221
	v_mov_b32_e32 v63, v221
.LmixA_m1:
	s_add_i32 s23, s22, 64
	s_cmp_ge_i32 s23, s87
	s_cbranch_scc0 .LmixA_m4
	v_mov_b32_e32 v0, v221
	v_mov_b32_e32 v1, v221
	v_mov_b32_e32 v2, v221
	v_mov_b32_e32 v3, v221
	v_mov_b32_e32 v4, v221
	v_mov_b32_e32 v5, v221
	v_mov_b32_e32 v6, v221
	v_mov_b32_e32 v7, v221
	v_mov_b32_e32 v8, v221
	v_mov_b32_e32 v9, v221
	v_mov_b32_e32 v10, v221
	v_mov_b32_e32 v11, v221
	v_mov_b32_e32 v12, v221
	v_mov_b32_e32 v13, v221
	v_mov_b32_e32 v14, v221
	v_mov_b32_e32 v15, v221
.LmixA_m4:
	s_add_i32 s23, s22, 32
	s_cmp_ge_i32 s23, s87
	s_cbranch_scc0 .LmixA_m3
	v_mov_b32_e32 v16, v221
	v_mov_b32_e32 v17, v221
	v_mov_b32_e32 v18, v221
	v_mov_b32_e32 v19, v221
	v_mov_b32_e32 v20, v221
	v_mov_b32_e32 v21, v221
	v_mov_b32_e32 v22, v221
	v_mov_b32_e32 v23, v221
	v_mov_b32_e32 v24, v221
	v_mov_b32_e32 v25, v221
	v_mov_b32_e32 v26, v221
	v_mov_b32_e32 v27, v221
	v_mov_b32_e32 v28, v221
	v_mov_b32_e32 v29, v221
	v_mov_b32_e32 v30, v221
	v_mov_b32_e32 v31, v221
.LmixA_m3:
	s_branch .LmixA_fast
